# mstate prompt task: k and V fragment loads hoisted to task top (22 loads in flight with gate loads)
# speedup vs baseline: 1.0098x; 1.0098x over previous
; #define LAS __attribute__((address_space(3)))
; __device__ __forceinline__ float fexp(float x) { return __builtin_amdgcn_exp2f(x * LOG2E); }
; #define LDS_WAIT() asm volatile("s_waitcnt lgkmcnt(0)" ::: "memory")
; __device__ __forceinline__ s16x8 pack8(const float (&x)[8]) { u32x4 p; p.x = pk2(x[0], x[1]); p.y = pk2(x[2], x[3]); p.z = pk2(x[4], x[5]); p.w = pk2(x[6], x[7]); return __builtin_bit_cast(s16x8, p); }
; __device__ __forceinline__ void unpack8(u32x4 v, float (&x)[8]) { x[0] = bflo(v.x); x[1] = bfhi(v.x); x[2] = bflo(v.y); x[3] = bfhi(v.y); x[4] = bflo(v.z); x[5] = bfhi(v.z); x[6] = bflo(v.w); x[7] = bfhi(v.w); }
;     __device__ __forceinline__ bf16* KVt() const { return (bf16*)(ws + WS_KVT); }
; template <bool SAMPLE>
; __device__ __forceinline__ void mstate_task(Ctx& C, int l, int unit, int h, int dblk, LAS float* wbuf) {
;     ...
;     const float li = valid ? C.GATES()[(grow0 + lane) * 8 + h] : -1e30f, lf = valid ? C.GATES()[(grow0 + lane) * 8 + 4 + h] : 0.f;
;     const float bc = scan_add(lf, lane), Bc = __shfl(bc, L - 1);
;     const float uu = valid ? Bc - bc + li : -1e30f, Mc = wave_max(uu);
;     const float w = valid ? fexp(uu - Mc) : 0.f;
;     wbuf[lane] = w;
;     LDS_WAIT();
;     const int d = 32 * dblk + r;
;     const bf16* krow = C.KVt() + (size_t)(R_KM + h * 128 + d) * MT + grow0;
;     float dn = 0.f; s16x8 Bf[NKS];
;     { u32x4 kq[NKS];
; #pragma unroll
;       for (int ks = 0; ks < NKS; ++ks) kq[ks] = *(const u32x4*)(krow + 16 * ks + 8 * hi);
; #pragma unroll
;       for (int ks = 0; ks < NKS; ++ks) { const int s0 = 16 * ks + 8 * hi;
;         float kc[8]; unpack8(kq[ks], kc);
;         const f32x4 w0 = *(const LAS f32x4*)(wbuf + s0), w1 = *(const LAS f32x4*)(wbuf + s0 + 4);
; #pragma unroll
;         for (int e = 0; e < 8; ++e) { kc[e] *= (e < 4 ? w0[e] : w1[e - 4]); dn += kc[e]; }
;         Bf[ks] = pack8(kc); } }
;     bf16* dcp = (SAMPLE ? C.DCS() + (size_t)(slot - NSLOT_P) * 16384 : C.DC() + (size_t)slot * 16384);
; #pragma unroll
;     for (int vb = 0; vb < 4; ++vb) {
;         f32x16 acc;
; #pragma unroll
;         for (int i = 0; i < 16; ++i) acc[i] = 0.f;
;         const bf16* vrow = C.KVt() + (size_t)(R_VM + h * 128 + 32 * vb + r) * MT + grow0 + 8 * hi;
;         s16x8 af[NKS];
; #pragma unroll
;         for (int ks = 0; ks < NKS; ++ks) af[ks] = *(const s16x8*)(vrow + 16 * ks);
.LBB0_622:
	s_mov_b64 s[2:3], -1
	v_and_b32_e32 v40, 63, v202
	v_lshrrev_b32_e32 v41, 5, v40
	v_and_b32_e32 v0, 32, v202
	v_readfirstlane_b32 s23, v202
	s_cmp_gt_i32 s72, 63
	v_and_b32_e32 v42, 31, v202
	v_cmp_eq_u32_e64 s[12:13], 0, v40
	v_cmp_gt_u32_e64 s[10:11], 2, v40
	v_cmp_gt_u32_e64 s[8:9], 4, v40
	v_cmp_gt_u32_e64 s[6:7], 8, v40
	v_cmp_gt_u32_e64 s[4:5], 16, v40
	v_cmp_gt_u32_e32 vcc, 32, v40
	v_lshl_add_u32 v44, v40, 2, s22
	v_lshlrev_b32_e32 v192, 4, v41
	v_add_u32_e32 v43, s22, v0
	s_cbranch_scc0 .LBB0_628
	s_sub_i32 s2, s72, 64
	s_lshr_b32 s19, s2, 1
	s_lshl_b32 s2, s72, 1
	s_and_b32 s2, s2, 2
	s_ashr_i32 s3, s23, 8
	s_add_i32 s20, s3, s2
	s_lshl_b32 s2, s19, 2
	s_add_i32 s18, s20, s2
	v_lshl_or_b32 v0, s19, 6, v40
	s_waitcnt lgkmcnt(0)
	v_mov_b32_e32 v1, v193
	v_readlane_b32 s2, v254, 55
	s_ashr_i32 s21, s20, 31
	v_lshlrev_b64 v[0:1], 5, v[0:1]
	v_readlane_b32 s3, v254, 56
	s_bfe_u32 s34, s23, 0x20006
	v_lshl_or_b32 v47, s34, 5, v42
	v_lshl_add_u64 v[2:3], s[2:3], 0, v[0:1]
	s_lshl_b64 s[2:3], s[20:21], 2
	v_lshl_add_u64 v[0:1], s[90:91], 0, v[0:1]
	v_lshl_add_u64 v[2:3], v[2:3], 0, s[2:3]
	v_lshl_add_u64 v[0:1], v[0:1], 0, s[2:3]
	s_mov_b32 s2, 0x1f518000
	v_add_co_u32_e64 v0, s[2:3], s2, v0
	global_load_dword v2, v[2:3], off
	s_nop 0
	v_addc_co_u32_e64 v1, s[2:3], 0, v1, s[2:3]
	global_load_dword v0, v[0:1], off offset:16
	v_and_b32_e32 v1, 64, v220
	v_add_u32_e32 v3, -1, v220
	v_cmp_lt_i32_e64 s[2:3], v3, v1
	s_lshl_b32 s78, s19, 7
	s_ashr_i32 s19, s18, 31
	v_cndmask_b32_e64 v3, v3, v220, s[2:3]
	v_lshlrev_b32_e32 v3, 2, v3
	v_lshlrev_b32_e32 v34, 1, v47
	v_lshl_or_b32 v38, v41, 10, v34
	v_mov_b32_e32 v39, v193
	s_lshl_b32 s2, s20, 7
	s_add_i32 s3, s2, 0x400
	v_or_b32_e32 v84, s3, v47
	s_add_i32 s3, s2, 0x200
	v_or_b32_e32 v85, s3, v42
	v_mov_b64_e32 v[86:87], s[74:75]
	s_nop 0
	v_mad_i64_i32 v[88:89], s[2:3], v84, s81, v[86:87]
	v_lshl_add_u64 v[88:89], v[88:89], 0, s[78:79]
	v_lshl_add_u64 v[88:89], v[88:89], 0, v[192:193]
	global_load_dwordx4 v[92:95], v[88:89], off
	global_load_dwordx4 v[96:99], v[88:89], off offset:32
	global_load_dwordx4 v[100:103], v[88:89], off offset:64
	global_load_dwordx4 v[104:107], v[88:89], off offset:96
	s_add_u32 s2, s74, s78
	s_addc_u32 s3, s75, 0
	v_lshl_add_u64 v[90:91], s[2:3], 0, v[192:193]
	v_mad_i64_i32 v[62:63], s[2:3], v85, s81, v[90:91]
	v_or_b32_e32 v78, 32, v85
	v_mad_i64_i32 v[64:65], s[2:3], v78, s81, v[90:91]
	v_or_b32_e32 v78, 64, v85
	v_mad_i64_i32 v[66:67], s[2:3], v78, s81, v[90:91]
	v_or_b32_e32 v78, 0x60, v85
	v_mad_i64_i32 v[68:69], s[2:3], v78, s81, v[90:91]
	global_load_dwordx4 v[126:129], v[62:63], off
	global_load_dwordx4 v[130:133], v[62:63], off offset:32
	global_load_dwordx4 v[134:137], v[62:63], off offset:64
	global_load_dwordx4 v[138:141], v[62:63], off offset:96
	global_load_dwordx4 v[142:145], v[64:65], off
	global_load_dwordx4 v[146:149], v[64:65], off offset:32
	global_load_dwordx4 v[150:153], v[64:65], off offset:64
	global_load_dwordx4 v[154:157], v[64:65], off offset:96
	global_load_dwordx4 v[158:161], v[66:67], off
	global_load_dwordx4 v[162:165], v[66:67], off offset:32
	global_load_dwordx4 v[166:169], v[66:67], off offset:64
	global_load_dwordx4 v[170:173], v[66:67], off offset:96
	global_load_dwordx4 v[174:177], v[68:69], off
	global_load_dwordx4 v[178:181], v[68:69], off offset:32
	global_load_dwordx4 v[70:73], v[68:69], off offset:64
	global_load_dwordx4 v[74:77], v[68:69], off offset:96
	s_waitcnt vmcnt(20)
	ds_bpermute_b32 v3, v3, v0
	s_waitcnt lgkmcnt(0)
	v_add_f32_e32 v3, v0, v3
	v_cndmask_b32_e64 v0, v3, v0, s[12:13]
	v_add_u32_e32 v3, -2, v220
	v_cmp_lt_i32_e64 s[2:3], v3, v1
	s_nop 1
	v_cndmask_b32_e64 v3, v3, v220, s[2:3]
	v_lshlrev_b32_e32 v3, 2, v3
	ds_bpermute_b32 v3, v3, v0
	s_waitcnt lgkmcnt(0)
	v_add_f32_e32 v3, v0, v3
	v_cndmask_b32_e64 v0, v3, v0, s[10:11]
	v_add_u32_e32 v3, -4, v220
	v_cmp_lt_i32_e64 s[2:3], v3, v1
	s_nop 1
	v_cndmask_b32_e64 v3, v3, v220, s[2:3]
	v_lshlrev_b32_e32 v3, 2, v3
	ds_bpermute_b32 v3, v3, v0
	s_waitcnt lgkmcnt(0)
	v_add_f32_e32 v3, v0, v3
	v_cndmask_b32_e64 v0, v3, v0, s[8:9]
	v_add_u32_e32 v3, -8, v220
	v_cmp_lt_i32_e64 s[2:3], v3, v1
	s_nop 1
	v_cndmask_b32_e64 v3, v3, v220, s[2:3]
	v_lshlrev_b32_e32 v3, 2, v3
	ds_bpermute_b32 v3, v3, v0
	s_waitcnt lgkmcnt(0)
	v_add_f32_e32 v3, v0, v3
	v_cndmask_b32_e64 v0, v3, v0, s[6:7]
	v_add_u32_e32 v3, -16, v220
	v_cmp_lt_i32_e64 s[2:3], v3, v1
	v_readlane_b32 s6, v254, 53
	v_readlane_b32 s7, v254, 54
	v_cndmask_b32_e64 v3, v3, v220, s[2:3]
	v_lshlrev_b32_e32 v3, 2, v3
	ds_bpermute_b32 v3, v3, v0
	s_waitcnt lgkmcnt(0)
	v_add_f32_e32 v3, v0, v3
	v_cndmask_b32_e64 v0, v3, v0, s[4:5]
	v_subrev_u32_e32 v3, 32, v220
	v_cmp_lt_i32_e64 s[2:3], v3, v1
	v_add_u32_e32 v1, 64, v1
	s_nop 0
	v_cndmask_b32_e64 v3, v3, v220, s[2:3]
	v_lshlrev_b32_e32 v3, 2, v3
	ds_bpermute_b32 v3, v3, v0
	s_waitcnt lgkmcnt(0)
	v_add_f32_e32 v3, v0, v3
	v_cndmask_b32_e32 v0, v3, v0, vcc
	v_bfrev_b32_e32 v3, 0.5
	v_lshl_or_b32 v3, v220, 2, v3
	ds_bpermute_b32 v45, v3, v0
	v_xor_b32_e32 v3, 2, v220
	s_waitcnt lgkmcnt(0)
	v_sub_f32_e32 v0, v45, v0
	v_add_f32_e32 v0, v2, v0
	v_xor_b32_e32 v2, 1, v220
	v_cmp_lt_i32_e64 s[2:3], v2, v1
	s_nop 1
	v_cndmask_b32_e64 v2, v220, v2, s[2:3]
	v_lshlrev_b32_e32 v2, 2, v2
	ds_bpermute_b32 v2, v2, v0
	v_cmp_lt_i32_e64 s[2:3], v3, v1
	s_waitcnt lgkmcnt(0)
	v_max_f32_e32 v2, v2, v2
	v_cndmask_b32_e64 v3, v220, v3, s[2:3]
	v_max_f32_e32 v2, v0, v2
	v_lshlrev_b32_e32 v3, 2, v3
	ds_bpermute_b32 v3, v3, v2
	s_waitcnt lgkmcnt(0)
	v_max_f32_e32 v3, v3, v3
	v_max_f32_e32 v2, v2, v3
	v_xor_b32_e32 v3, 4, v220
	v_cmp_lt_i32_e64 s[2:3], v3, v1
	s_nop 1
	v_cndmask_b32_e64 v3, v220, v3, s[2:3]
	v_lshlrev_b32_e32 v3, 2, v3
	ds_bpermute_b32 v3, v3, v2
	s_waitcnt lgkmcnt(0)
; #define LAS __attribute__((address_space(3)))
; __device__ __forceinline__ float fexp(float x) { return __builtin_amdgcn_exp2f(x * LOG2E); }
; #define LDS_WAIT() asm volatile("s_waitcnt lgkmcnt(0)" ::: "memory")
; #define MFMA32(a, b, c) __builtin_amdgcn_mfma_f32_32x32x16_bf16((a), (b), (c), 0, 0, 0)
; __device__ __forceinline__ s16x8 pack8(const float (&x)[8]) { u32x4 p; p.x = pk2(x[0], x[1]); p.y = pk2(x[2], x[3]); p.z = pk2(x[4], x[5]); p.w = pk2(x[6], x[7]); return __builtin_bit_cast(s16x8, p); }
; __device__ __forceinline__ void unpack8(u32x4 v, float (&x)[8]) { x[0] = bflo(v.x); x[1] = bfhi(v.x); x[2] = bflo(v.y); x[3] = bfhi(v.y); x[4] = bflo(v.z); x[5] = bfhi(v.z); x[6] = bflo(v.w); x[7] = bfhi(v.w); }
;     __device__ __forceinline__ bf16* KVt() const { return (bf16*)(ws + WS_KVT); }
; template <bool SAMPLE>
; __device__ __forceinline__ void mstate_task(Ctx& C, int l, int unit, int h, int dblk, LAS float* wbuf) {
;     ...
;     const float uu = valid ? Bc - bc + li : -1e30f, Mc = wave_max(uu);
;     const float w = valid ? fexp(uu - Mc) : 0.f;
;     wbuf[lane] = w;
;     LDS_WAIT();
;     const int d = 32 * dblk + r;
;     const bf16* krow = C.KVt() + (size_t)(R_KM + h * 128 + d) * MT + grow0;
;     float dn = 0.f; s16x8 Bf[NKS];
;     { u32x4 kq[NKS];
; #pragma unroll
;       for (int ks = 0; ks < NKS; ++ks) kq[ks] = *(const u32x4*)(krow + 16 * ks + 8 * hi);
; #pragma unroll
;       for (int ks = 0; ks < NKS; ++ks) { const int s0 = 16 * ks + 8 * hi;
;         float kc[8]; unpack8(kq[ks], kc);
;         const f32x4 w0 = *(const LAS f32x4*)(wbuf + s0), w1 = *(const LAS f32x4*)(wbuf + s0 + 4);
; #pragma unroll
;         for (int e = 0; e < 8; ++e) { kc[e] *= (e < 4 ? w0[e] : w1[e - 4]); dn += kc[e]; }
;         Bf[ks] = pack8(kc); } }
;     bf16* dcp = (SAMPLE ? C.DCS() + (size_t)(slot - NSLOT_P) * 16384 : C.DC() + (size_t)slot * 16384);
; #pragma unroll
;     for (int vb = 0; vb < 4; ++vb) {
;         f32x16 acc;
; #pragma unroll
;         for (int i = 0; i < 16; ++i) acc[i] = 0.f;
;         const bf16* vrow = C.KVt() + (size_t)(R_VM + h * 128 + 32 * vb + r) * MT + grow0 + 8 * hi;
;         s16x8 af[NKS];
; #pragma unroll
;         for (int ks = 0; ks < NKS; ++ks) af[ks] = *(const s16x8*)(vrow + 16 * ks);
; #pragma unroll
;         for (int ks = 0; ks < NKS; ++ks) acc = MFMA32(af[ks], Bf[ks], acc);
	v_max_f32_e32 v3, v3, v3
	v_max_f32_e32 v2, v2, v3
	v_xor_b32_e32 v3, 8, v220
	v_cmp_lt_i32_e64 s[2:3], v3, v1
	s_nop 1
	v_cndmask_b32_e64 v3, v220, v3, s[2:3]
	v_lshlrev_b32_e32 v3, 2, v3
	ds_bpermute_b32 v3, v3, v2
	s_waitcnt lgkmcnt(0)
	v_max_f32_e32 v3, v3, v3
	v_max_f32_e32 v2, v2, v3
	v_xor_b32_e32 v3, 16, v220
	v_cmp_lt_i32_e64 s[2:3], v3, v1
	s_nop 1
	v_cndmask_b32_e64 v3, v220, v3, s[2:3]
	v_lshlrev_b32_e32 v3, 2, v3
	ds_bpermute_b32 v3, v3, v2
	s_waitcnt lgkmcnt(0)
	v_max_f32_e32 v3, v3, v3
	v_max_f32_e32 v2, v2, v3
	v_xor_b32_e32 v3, 32, v220
	v_cmp_lt_i32_e64 s[2:3], v3, v1
	s_nop 1
	v_cndmask_b32_e64 v1, v220, v3, s[2:3]
	v_lshlrev_b32_e32 v48, 2, v1
	ds_bpermute_b32 v1, v48, v2
	s_lshl_b32 s2, s20, 7
	s_add_i32 s3, s2, 0x400
	s_waitcnt lgkmcnt(0)
	v_max_f32_e32 v1, v1, v1
	v_max_f32_e32 v46, v2, v1
	v_sub_f32_e32 v0, v0, v46
	v_mul_f32_e32 v0, 0x3fb8aa3b, v0
	v_exp_f32_e32 v0, v0
	v_or_b32_e32 v2, s3, v47
	ds_write_b32 v44, v0 offset:16384
	v_mov_b64_e32 v[0:1], s[74:75]
	v_mad_i64_i32 v[0:1], s[4:5], v2, s81, v[0:1]
	v_lshl_add_u64 v[0:1], v[0:1], 0, s[78:79]
	s_waitcnt lgkmcnt(0)
	v_lshl_add_u64 v[12:13], v[0:1], 0, v[192:193]
	s_waitcnt vmcnt(16)
	v_mov_b64_e32 v[0:1], v[92:93]
	v_mov_b64_e32 v[2:3], v[94:95]
	v_mov_b64_e32 v[4:5], v[96:97]
	v_mov_b64_e32 v[6:7], v[98:99]
	v_mov_b64_e32 v[8:9], v[100:101]
	v_mov_b64_e32 v[10:11], v[102:103]
	v_mov_b64_e32 v[12:13], v[104:105]
	v_mov_b64_e32 v[14:15], v[106:107]
	s_nop 0
	ds_read_b128 v[16:19], v43 offset:16384
	ds_read_b128 v[20:23], v43 offset:16400
	s_lshl_b64 s[4:5], s[18:19], 15
	s_add_u32 s4, s6, s4
	s_addc_u32 s5, s7, s5
	s_addk_i32 s2, 0x200
	v_lshl_add_u64 v[34:35], s[4:5], 0, v[38:39]
	v_lshlrev_b32_e32 v24, 16, v0
	v_and_b32_e32 v25, 0xffff0000, v0
	s_waitcnt lgkmcnt(1)
	v_pk_mul_f32 v[16:17], v[16:17], v[24:25]
	v_and_b32_e32 v25, 0xffff0000, v4
	v_add_f32_e32 v0, 0, v16
	v_add_f32_e32 v24, v17, v0
	v_lshlrev_b32_e32 v0, 16, v1
	v_and_b32_e32 v1, 0xffff0000, v1
	v_pk_mul_f32 v[0:1], v[18:19], v[0:1]
	v_and_b32_e32 v19, 0xffff0000, v2
	v_add_f32_e32 v18, v0, v24
	v_add_f32_e32 v24, v1, v18
	v_lshlrev_b32_e32 v18, 16, v2
	s_waitcnt lgkmcnt(0)
	v_pk_mul_f32 v[18:19], v[20:21], v[18:19]
	v_cvt_pk_bf16_f32 v16, v16, v17
	v_add_f32_e32 v2, v18, v24
	v_add_f32_e32 v20, v19, v2
	v_lshlrev_b32_e32 v2, 16, v3
	v_and_b32_e32 v3, 0xffff0000, v3
	v_pk_mul_f32 v[2:3], v[22:23], v[2:3]
	v_cvt_pk_bf16_f32 v17, v0, v1
	v_add_f32_e32 v20, v2, v20
	v_add_f32_e32 v26, v3, v20
	v_cvt_pk_bf16_f32 v18, v18, v19
	v_cvt_pk_bf16_f32 v19, v2, v3
	ds_read_b128 v[0:3], v43 offset:16448
	ds_read_b128 v[20:23], v43 offset:16464
	v_lshlrev_b32_e32 v24, 16, v4
	s_waitcnt lgkmcnt(1)
	v_pk_mul_f32 v[0:1], v[0:1], v[24:25]
	s_nop 0
	v_add_f32_e32 v4, v0, v26
	v_add_f32_e32 v24, v1, v4
	v_lshlrev_b32_e32 v4, 16, v5
	v_and_b32_e32 v5, 0xffff0000, v5
	v_pk_mul_f32 v[2:3], v[2:3], v[4:5]
	v_and_b32_e32 v5, 0xffff0000, v6
	v_add_f32_e32 v4, v2, v24
	v_add_f32_e32 v24, v3, v4
	v_lshlrev_b32_e32 v4, 16, v6
	s_waitcnt lgkmcnt(0)
	v_pk_mul_f32 v[4:5], v[20:21], v[4:5]
	v_cvt_pk_bf16_f32 v21, v2, v3
	v_add_f32_e32 v6, v4, v24
	v_add_f32_e32 v20, v5, v6
	v_lshlrev_b32_e32 v6, 16, v7
	v_and_b32_e32 v7, 0xffff0000, v7
	v_pk_mul_f32 v[6:7], v[22:23], v[6:7]
	v_cvt_pk_bf16_f32 v22, v4, v5
	v_add_f32_e32 v20, v6, v20
	v_add_f32_e32 v26, v7, v20
	v_cvt_pk_bf16_f32 v20, v0, v1
	v_cvt_pk_bf16_f32 v23, v6, v7
	ds_read_b128 v[0:3], v43 offset:16512
	ds_read_b128 v[4:7], v43 offset:16528
	v_lshlrev_b32_e32 v24, 16, v8
	v_and_b32_e32 v25, 0xffff0000, v8
	s_waitcnt lgkmcnt(1)
	v_pk_mul_f32 v[0:1], v[0:1], v[24:25]
	s_nop 0
	v_add_f32_e32 v8, v0, v26
	v_add_f32_e32 v24, v1, v8
	v_lshlrev_b32_e32 v8, 16, v9
	v_and_b32_e32 v9, 0xffff0000, v9
	v_pk_mul_f32 v[2:3], v[2:3], v[8:9]
	v_and_b32_e32 v9, 0xffff0000, v10
	v_add_f32_e32 v8, v2, v24
	v_add_f32_e32 v24, v3, v8
	v_lshlrev_b32_e32 v8, 16, v10
	s_waitcnt lgkmcnt(0)
	v_pk_mul_f32 v[4:5], v[4:5], v[8:9]
	v_and_b32_e32 v9, 0xffff0000, v11
	v_add_f32_e32 v8, v4, v24
	v_add_f32_e32 v10, v5, v8
	v_lshlrev_b32_e32 v8, 16, v11
	v_pk_mul_f32 v[6:7], v[6:7], v[8:9]
	v_cvt_pk_bf16_f32 v24, v0, v1
	v_add_f32_e32 v8, v6, v10
	v_add_f32_e32 v10, v7, v8
	v_cvt_pk_bf16_f32 v25, v2, v3
	v_cvt_pk_bf16_f32 v26, v4, v5
	v_cvt_pk_bf16_f32 v27, v6, v7
	ds_read_b128 v[0:3], v43 offset:16576
	ds_read_b128 v[4:7], v43 offset:16592
	v_lshlrev_b32_e32 v8, 16, v12
	v_and_b32_e32 v9, 0xffff0000, v12
	s_waitcnt lgkmcnt(1)
	v_pk_mul_f32 v[0:1], v[0:1], v[8:9]
	s_nop 0
	v_add_f32_e32 v8, v0, v10
	v_add_f32_e32 v10, v1, v8
	v_lshlrev_b32_e32 v8, 16, v13
	v_and_b32_e32 v9, 0xffff0000, v13
	v_pk_mul_f32 v[2:3], v[2:3], v[8:9]
	v_and_b32_e32 v9, 0xffff0000, v14
	v_add_f32_e32 v8, v2, v10
	v_add_f32_e32 v10, v3, v8
	v_lshlrev_b32_e32 v8, 16, v14
	s_waitcnt lgkmcnt(0)
	v_pk_mul_f32 v[4:5], v[4:5], v[8:9]
	v_and_b32_e32 v9, 0xffff0000, v15
	v_add_f32_e32 v8, v4, v10
	v_add_f32_e32 v10, v5, v8
	v_lshlrev_b32_e32 v8, 16, v15
	v_pk_mul_f32 v[32:33], v[6:7], v[8:9]
	v_cvt_pk_bf16_f32 v30, v4, v5
	v_add_f32_e32 v49, v32, v10
	v_cvt_pk_bf16_f32 v31, v32, v33
	v_or_b32_e32 v32, s2, v42
	s_add_u32 s2, s74, s78
	s_addc_u32 s3, s75, 0
	v_lshl_add_u64 v[36:37], s[2:3], 0, v[192:193]
	v_mad_i64_i32 v[4:5], s[2:3], v32, s81, v[36:37]
	v_cvt_pk_bf16_f32 v28, v0, v1
	v_cvt_pk_bf16_f32 v29, v2, v3
	s_waitcnt vmcnt(15)
	v_mfma_f32_32x32x16_bf16 v[0:15], v[126:129], v[16:19], 0
	s_waitcnt vmcnt(14)
	v_mfma_f32_32x32x16_bf16 v[0:15], v[130:133], v[20:23], v[0:15]
	s_waitcnt vmcnt(13)
	v_mfma_f32_32x32x16_bf16 v[0:15], v[134:137], v[24:27], v[0:15]
	s_waitcnt vmcnt(12)
; __device__ __forceinline__ bf16 f2bf(float f) { return (bf16)(pk2(f, 0.f) & 0xffffu); }
; #define MFMA32(a, b, c) __builtin_amdgcn_mfma_f32_32x32x16_bf16((a), (b), (c), 0, 0, 0)
; template <bool SAMPLE>
; __device__ __forceinline__ void mstate_task(Ctx& C, int l, int unit, int h, int dblk, LAS float* wbuf) {
;     ...
;         for (int ks = 0; ks < NKS; ++ks) af[ks] = *(const s16x8*)(vrow + 16 * ks);
; #pragma unroll
;         for (int ks = 0; ks < NKS; ++ks) acc = MFMA32(af[ks], Bf[ks], acc);
; #pragma unroll
;         for (int i = 0; i < 16; ++i) { const int v = 32 * vb + 8 * (i >> 2) + 4 * hi + (i & 3); dcp[v * 128 + d] = f2bf(acc[i]); }
	v_mfma_f32_32x32x16_bf16 v[0:15], v[138:141], v[28:31], v[0:15]
	s_nop 11
	v_cvt_pk_bf16_f32 v0, v0, s0
	global_store_short v38, v0, s[4:5]
	v_cvt_pk_bf16_f32 v0, v1, s0
	global_store_short v38, v0, s[4:5] offset:256
	v_cvt_pk_bf16_f32 v0, v2, s0
	global_store_short v38, v0, s[4:5] offset:512
	v_cvt_pk_bf16_f32 v0, v3, s0
	global_store_short v38, v0, s[4:5] offset:768
	v_cvt_pk_bf16_f32 v0, v4, s0
	global_store_short v38, v0, s[4:5] offset:2048
	v_cvt_pk_bf16_f32 v0, v5, s0
	global_store_short v38, v0, s[4:5] offset:2304
	v_cvt_pk_bf16_f32 v0, v6, s0
	global_store_short v38, v0, s[4:5] offset:2560
	v_cvt_pk_bf16_f32 v0, v7, s0
	global_store_short v38, v0, s[4:5] offset:2816
	v_add_co_u32_e64 v0, s[2:3], s60, v34
	v_cvt_pk_bf16_f32 v2, v8, s0
	s_nop 0
	v_addc_co_u32_e64 v1, s[2:3], 0, v35, s[2:3]
	v_add_co_u32_e64 v38, s[2:3], s36, v34
	s_nop 1
	v_addc_co_u32_e64 v39, s[2:3], 0, v35, s[2:3]
	global_store_short v[38:39], v2, off offset:-4096
	v_cvt_pk_bf16_f32 v2, v9, s0
	global_store_short v[0:1], v2, off offset:256
	v_cvt_pk_bf16_f32 v2, v10, s0
	global_store_short v[0:1], v2, off offset:512
	v_cvt_pk_bf16_f32 v2, v11, s0
	global_store_short v[0:1], v2, off offset:768
	v_cvt_pk_bf16_f32 v2, v12, s0
	global_store_short v[0:1], v2, off offset:2048
	v_cvt_pk_bf16_f32 v2, v13, s0
	global_store_short v[0:1], v2, off offset:2304
	v_cvt_pk_bf16_f32 v2, v14, s0
	global_store_short v[0:1], v2, off offset:2560
	v_cvt_pk_bf16_f32 v2, v15, s0
	global_store_short v[0:1], v2, off offset:2816
	v_or_b32_e32 v0, 32, v32
	v_mad_i64_i32 v[0:1], s[2:3], v0, s81, v[36:37]
	s_waitcnt vmcnt(27)
	v_mfma_f32_32x32x16_bf16 v[0:15], v[142:145], v[16:19], 0
	s_waitcnt vmcnt(26)
	v_mfma_f32_32x32x16_bf16 v[0:15], v[146:149], v[20:23], v[0:15]
	s_waitcnt vmcnt(25)
	v_mfma_f32_32x32x16_bf16 v[0:15], v[150:153], v[24:27], v[0:15]
	s_waitcnt vmcnt(24)
	v_mfma_f32_32x32x16_bf16 v[0:15], v[154:157], v[28:31], v[0:15]
	s_nop 11
	v_cvt_pk_bf16_f32 v0, v0, s0
	global_store_short v[38:39], v0, off
	v_cvt_pk_bf16_f32 v0, v1, s0
	global_store_short v[38:39], v0, off offset:256
	v_cvt_pk_bf16_f32 v0, v2, s0
	global_store_short v[38:39], v0, off offset:512
	v_cvt_pk_bf16_f32 v0, v3, s0
	global_store_short v[38:39], v0, off offset:768
	v_cvt_pk_bf16_f32 v0, v4, s0
	global_store_short v[38:39], v0, off offset:2048
	v_cvt_pk_bf16_f32 v0, v5, s0
	global_store_short v[38:39], v0, off offset:2304
	v_cvt_pk_bf16_f32 v0, v6, s0
	global_store_short v[38:39], v0, off offset:2560
	v_cvt_pk_bf16_f32 v0, v7, s0
	global_store_short v[38:39], v0, off offset:2816
	v_add_co_u32_e64 v0, s[2:3], s38, v34
	v_cvt_pk_bf16_f32 v2, v8, s0
	s_nop 0
	v_addc_co_u32_e64 v1, s[2:3], 0, v35, s[2:3]
	s_movk_i32 s2, 0x4000
	s_nop 0
	v_add_co_u32_e64 v38, s[2:3], s2, v34
	s_nop 1
	v_addc_co_u32_e64 v39, s[2:3], 0, v35, s[2:3]
	global_store_short v[38:39], v2, off offset:-4096
	v_cvt_pk_bf16_f32 v2, v9, s0
	global_store_short v[0:1], v2, off offset:256
	v_cvt_pk_bf16_f32 v2, v10, s0
	global_store_short v[0:1], v2, off offset:512
	v_cvt_pk_bf16_f32 v2, v11, s0
	global_store_short v[0:1], v2, off offset:768
	v_cvt_pk_bf16_f32 v2, v12, s0
	global_store_short v[0:1], v2, off offset:2048
	v_cvt_pk_bf16_f32 v2, v13, s0
	global_store_short v[0:1], v2, off offset:2304
	v_cvt_pk_bf16_f32 v2, v14, s0
	global_store_short v[0:1], v2, off offset:2560
	v_cvt_pk_bf16_f32 v2, v15, s0
	global_store_short v[0:1], v2, off offset:2816
	v_or_b32_e32 v0, 64, v32
	v_mad_i64_i32 v[4:5], s[2:3], v0, s81, v[36:37]
	s_waitcnt vmcnt(39)
	v_mfma_f32_32x32x16_bf16 v[0:15], v[158:161], v[16:19], 0
	s_waitcnt vmcnt(38)
	v_mfma_f32_32x32x16_bf16 v[0:15], v[162:165], v[20:23], v[0:15]
	s_waitcnt vmcnt(37)
; __device__ __forceinline__ bf16 f2bf(float f) { return (bf16)(pk2(f, 0.f) & 0xffffu); }
; #define MFMA32(a, b, c) __builtin_amdgcn_mfma_f32_32x32x16_bf16((a), (b), (c), 0, 0, 0)
;     __device__ __forceinline__ float* DN() const { return (float*)(ws + WS_DN); }
; template <bool SAMPLE>
; __device__ __forceinline__ void mstate_task(Ctx& C, int l, int unit, int h, int dblk, LAS float* wbuf) {
;     ...
; #pragma unroll
;         for (int ks = 0; ks < NKS; ++ks) acc = MFMA32(af[ks], Bf[ks], acc);
; #pragma unroll
;         for (int i = 0; i < 16; ++i) { const int v = 32 * vb + 8 * (i >> 2) + 4 * hi + (i & 3); dcp[v * 128 + d] = f2bf(acc[i]); }
;     }
;     dn += __shfl_xor(dn, 32);
;     if (hi == 0) C.DN()[(size_t)slot * 128 + d] = dn;
	v_mfma_f32_32x32x16_bf16 v[0:15], v[166:169], v[24:27], v[0:15]
	s_waitcnt vmcnt(36)
	v_mfma_f32_32x32x16_bf16 v[0:15], v[170:173], v[28:31], v[0:15]
	s_nop 11
	v_cvt_pk_bf16_f32 v0, v0, s0
	global_store_short v[38:39], v0, off
	v_cvt_pk_bf16_f32 v0, v1, s0
	global_store_short v[38:39], v0, off offset:256
	v_cvt_pk_bf16_f32 v0, v2, s0
	global_store_short v[38:39], v0, off offset:512
	v_cvt_pk_bf16_f32 v0, v3, s0
	global_store_short v[38:39], v0, off offset:768
	v_cvt_pk_bf16_f32 v0, v4, s0
	global_store_short v[38:39], v0, off offset:2048
	v_cvt_pk_bf16_f32 v0, v5, s0
	global_store_short v[38:39], v0, off offset:2304
	v_cvt_pk_bf16_f32 v0, v6, s0
	global_store_short v[38:39], v0, off offset:2560
	v_cvt_pk_bf16_f32 v0, v7, s0
	global_store_short v[38:39], v0, off offset:2816
	v_add_co_u32_e64 v0, s[2:3], s35, v34
	v_cvt_pk_bf16_f32 v2, v8, s0
	s_nop 0
	v_addc_co_u32_e64 v1, s[2:3], 0, v35, s[2:3]
	v_add_co_u32_e64 v58, s[2:3], s93, v34
	s_nop 1
	v_addc_co_u32_e64 v59, s[2:3], 0, v35, s[2:3]
	global_store_short v[58:59], v2, off offset:-4096
	v_cvt_pk_bf16_f32 v2, v9, s0
	global_store_short v[0:1], v2, off offset:256
	v_cvt_pk_bf16_f32 v2, v10, s0
	global_store_short v[0:1], v2, off offset:512
	v_cvt_pk_bf16_f32 v2, v11, s0
	global_store_short v[0:1], v2, off offset:768
	v_cvt_pk_bf16_f32 v2, v12, s0
	global_store_short v[0:1], v2, off offset:2048
	v_cvt_pk_bf16_f32 v2, v13, s0
	global_store_short v[0:1], v2, off offset:2304
	v_cvt_pk_bf16_f32 v2, v14, s0
	global_store_short v[0:1], v2, off offset:2560
	v_cvt_pk_bf16_f32 v2, v15, s0
	global_store_short v[0:1], v2, off offset:2816
	v_or_b32_e32 v0, 0x60, v32
	v_mad_i64_i32 v[4:5], s[2:3], v0, s81, v[36:37]
	s_waitcnt vmcnt(51)
	v_mfma_f32_32x32x16_bf16 v[0:15], v[174:177], v[16:19], 0
	s_movk_i32 s2, 0x7000
	s_waitcnt vmcnt(50)
	v_mfma_f32_32x32x16_bf16 v[0:15], v[178:181], v[20:23], v[0:15]
	s_waitcnt vmcnt(49)
	v_mfma_f32_32x32x16_bf16 v[0:15], v[70:73], v[24:27], v[0:15]
	s_waitcnt vmcnt(48)
	v_mfma_f32_32x32x16_bf16 v[0:15], v[74:77], v[28:31], v[0:15]
	s_nop 11
	v_cvt_pk_bf16_f32 v0, v0, s0
	global_store_short v[58:59], v0, off
	v_cvt_pk_bf16_f32 v0, v1, s0
	global_store_short v[58:59], v0, off offset:256
	v_cvt_pk_bf16_f32 v0, v2, s0
	global_store_short v[58:59], v0, off offset:512
	v_cvt_pk_bf16_f32 v0, v3, s0
	global_store_short v[58:59], v0, off offset:768
	v_cvt_pk_bf16_f32 v0, v4, s0
	global_store_short v[58:59], v0, off offset:2048
	v_cvt_pk_bf16_f32 v0, v5, s0
	global_store_short v[58:59], v0, off offset:2304
	v_cvt_pk_bf16_f32 v0, v6, s0
	global_store_short v[58:59], v0, off offset:2560
	v_cvt_pk_bf16_f32 v0, v7, s0
	global_store_short v[58:59], v0, off offset:2816
	v_add_co_u32_e64 v0, s[2:3], s2, v34
	v_cvt_pk_bf16_f32 v2, v8, s0
	s_nop 0
	v_addc_co_u32_e64 v1, s[2:3], 0, v35, s[2:3]
	global_store_short v[0:1], v2, off
	v_cvt_pk_bf16_f32 v2, v9, s0
	global_store_short v[0:1], v2, off offset:256
	v_cvt_pk_bf16_f32 v2, v10, s0
	global_store_short v[0:1], v2, off offset:512
	v_cvt_pk_bf16_f32 v2, v11, s0
	global_store_short v[0:1], v2, off offset:768
	v_cvt_pk_bf16_f32 v2, v12, s0
	global_store_short v[0:1], v2, off offset:2048
	v_cvt_pk_bf16_f32 v2, v13, s0
	global_store_short v[0:1], v2, off offset:2304
	v_cvt_pk_bf16_f32 v2, v14, s0
	global_store_short v[0:1], v2, off offset:2560
	v_cvt_pk_bf16_f32 v2, v15, s0
	global_store_short v[0:1], v2, off offset:2816
	v_add_f32_e32 v0, v33, v49
	ds_bpermute_b32 v1, v48, v0
	s_and_saveexec_b64 s[2:3], vcc
	s_cbranch_execz .LBB0_625
	s_lshl_b64 s[4:5], s[18:19], 9
	v_readlane_b32 s6, v254, 61
	v_readlane_b32 s7, v254, 62
	s_add_u32 s4, s6, s4
	s_waitcnt lgkmcnt(0)
	v_add_f32_e32 v0, v0, v1
	s_addc_u32 s5, s7, s5
	v_lshlrev_b32_e32 v1, 2, v47
	global_store_dword v1, v0, s[4:5]
